# one-way two-level P2a->P2b signal + first-segment RWKV workgroups defer their wait (per wave) to just before the first read of a pre-phase output
# baseline (speedup 1.0000x reference)
.LBB0_290:
	s_mov_b64 s[4:5], s[76:77]
	s_mov_b32 s1, s97
	s_mov_b32 s2, -1
	s_getreg_b32 s0, hwreg(HW_REG_XCC_ID, 0, 4)
	s_waitcnt vmcnt(0)
	s_nop 0
	v_mbcnt_lo_u32_b32 v0, s2, 0
	v_mbcnt_hi_u32_b32 v0, s2, v0
	v_lshl_or_b32 v0, s1, 6, v0
	v_cmp_eq_u32_e32 vcc, 0, v0
	s_barrier
	s_and_saveexec_b64 s[2:3], vcc
	s_cbranch_execz .LBB0_342
	s_load_dwordx2 s[6:7], s[4:5], 0xe0
	v_mov_b32_e32 v0, s78
	ds_read_b32 v2, v0
	v_mov_b32_e32 v0, s79
	ds_read_b32 v4, v0
	s_and_b32 s0, s0, 15
	s_lshl_b32 s1, s90, 12
	s_lshl_b32 s0, s0, 4
	v_mov_b32_e32 v1, 0
	v_mov_b32_e32 v0, 1
	s_waitcnt lgkmcnt(0)
	s_add_u32 s8, s6, s1
	s_addc_u32 s9, s7, 0
	s_add_u32 s8, s8, 0xc000
	s_addc_u32 s9, s9, 0
	s_add_u32 s10, s8, s0
	s_addc_u32 s11, s9, 0
	global_atomic_add v5, v1, v0, s[10:11] offset:3712 sc0
	s_waitcnt vmcnt(0)
	v_add_u32_e32 v5, 1, v5
	v_cmp_eq_u32_e32 vcc, v5, v2
	s_cbranch_vccz .Lsig_notlast
	buffer_wbl2 sc1
	s_waitcnt vmcnt(0)
	global_atomic_add v1, v2, s[8:9] offset:4032
.Lsig_notlast:
	s_cmpk_lt_u32 s96, 0xb0
	s_cbranch_scc1 .Lsig_skip
	s_cmpk_gt_u32 s96, 0xef
	s_cbranch_scc1 .Lsig_skip
	s_bitcmp0_b32 s96, 0
	s_cbranch_scc1 .Lsig_skip
	s_mov_b32 s0, 0
.Lsig_spin:
	global_load_dword v5, v1, s[8:9] offset:4032 sc1
	s_add_i32 s0, s0, 1
	s_waitcnt vmcnt(0)
	v_cmp_gt_u32_e32 vcc, 0x100, v5
	s_cbranch_vccz .Lsig_got
	s_sleep 1
	s_cmp_lt_u32 s0, 0x20000
	s_cbranch_scc1 .Lsig_spin

.LBB0_366:
	s_mov_b32 s0, -1
	s_add_i32 s61, s1, 0xffffff50
	v_mbcnt_lo_u32_b32 v0, s0, 0
	v_mbcnt_hi_u32_b32 v0, s0, v0
	v_or_b32_e32 v190, s43, v0
	s_mov_b32 s53, s93
	v_readfirstlane_b32 s0, v190
	s_ashr_i32 s60, s0, 6
	s_lshl_b32 s0, s61, 8
	s_and_b32 s52, s0, 0x7ffff800
	v_writelane_b32 v253, s54, 56
	s_and_b32 s96, s1, 1
	s_and_b32 s97, s60, 3
	s_lshl_b64 s[2:3], s[52:53], 10
	v_writelane_b32 v253, s55, 57
	s_add_u32 s54, s46, s2
	s_addc_u32 s55, s47, s3
	s_lshl_b32 s0, s61, 5
	v_and_b32_e32 v161, 63, v0
	s_and_b32 s2, s0, 0xc0
	v_mov_b32_e32 v0, v161
	s_cmp_lt_i32 s60, 4
	v_writelane_b32 v252, s46, 22
	s_cselect_b64 s[28:29], -1, 0
	s_cmp_gt_i32 s60, 3
	v_and_b32_e32 v1, 15, v0
	v_ashrrev_i32_e32 v0, 2, v0
	v_writelane_b32 v252, s47, 21
	s_mov_b32 s3, s93
	s_cselect_b64 s[30:31], -1, 0
	s_lshl_b32 s0, s97, 4
	v_and_b32_e32 v0, -4, v0
	s_mul_i32 s37, s52, 0x2200
	v_writelane_b32 v252, s2, 27
	v_readlane_b32 s98, v253, 19
	v_readlane_b32 s99, v253, 20
	v_readlane_b32 s100, v252, 17
	v_readlane_b32 s101, v252, 18
	s_lshl_b64 s[98:99], s[98:99], 2
	s_add_u32 s98, s100, s98
	s_addc_u32 s99, s101, s99
	s_lshl_b32 s100, s2, 2
	s_add_u32 s98, s98, s100
	s_addc_u32 s99, s99, 0
	s_or_b32 s100, s2, s84
	v_lshlrev_b32_e32 v192, 2, v161
	global_load_dword v196, v192, s[98:99] offset:1024
	global_load_dword v198, v192, s[98:99]
	global_load_dword v200, v192, s[98:99] offset:2048
	v_add_u32_e32 v192, s100, v161
	v_lshlrev_b32_e32 v192, 2, v192
	global_load_dword v197, v192, s[78:79]
	global_load_dword v201, v192, s[80:81]
	global_load_dword v192, v192, s[76:77]
	v_add_u32_e32 v0, s0, v0
	s_mul_hi_u32 s36, s52, 0x2200
	v_writelane_b32 v252, s3, 28
	v_cmp_eq_u32_e64 s[2:3], v0, v1
	s_add_u32 s38, s44, s37
	v_or_b32_e32 v2, 1, v0
	v_writelane_b32 v252, s2, 1
	s_addc_u32 s39, s45, s36
	s_lshl_b64 s[36:37], s[52:53], 9
	v_writelane_b32 v252, s3, 2
	v_cmp_eq_u32_e64 s[2:3], v2, v1
	s_add_u32 s36, s72, s36
	v_or_b32_e32 v4, 2, v0
	v_writelane_b32 v252, s2, 3
	v_or_b32_e32 v5, 3, v0
	v_or_b32_e32 v6, 16, v1
	s_addc_u32 s37, s73, s37
	v_writelane_b32 v252, s3, 4
	v_cmp_eq_u32_e64 s[6:7], v4, v1
	v_cmp_eq_u32_e64 s[8:9], v5, v1
	v_cmp_eq_u32_e64 s[10:11], v0, v6
	v_cmp_eq_u32_e64 s[12:13], v2, v6
	v_cmp_eq_u32_e64 s[14:15], v4, v6
	v_cmp_eq_u32_e64 s[16:17], v5, v6
	v_or_b32_e32 v6, 32, v1
	v_or_b32_e32 v1, 48, v1
	s_add_u32 s56, s36, 0xde00000
	v_cmp_eq_u32_e64 s[18:19], v0, v6
	v_cmp_eq_u32_e64 s[20:21], v2, v6
	v_cmp_eq_u32_e64 s[22:23], v4, v6
	v_cmp_eq_u32_e64 s[24:25], v5, v6
	v_cmp_eq_u32_e64 s[26:27], v0, v1
	v_cmp_eq_u32_e64 s[2:3], v2, v1
	v_cmp_eq_u32_e64 s[4:5], v4, v1
	v_cmp_eq_u32_e64 s[34:35], v5, v1
	v_writelane_b32 v252, s38, 29
	s_addc_u32 s57, s37, 0
	s_cmp_lg_u32 s96, 0
	s_cbranch_scc1 .Lsig_d_skip
	v_readlane_b32 s100, v253, 17
	v_mov_b32_e32 v8, 0
	v_mov_b32_e32 v10, 0
	s_lshl_b32 s100, s100, 2
	s_add_u32 s100, s72, s100
	s_addc_u32 s101, s73, 0
	s_add_u32 s100, s100, 0xc000
	s_addc_u32 s101, s101, 0
.Lsig_d_spin:
	global_load_dword v9, v8, s[100:101] offset:4032 sc1
	v_add_u32_e32 v10, 1, v10
	s_waitcnt vmcnt(0)
	v_cmp_gt_u32_e32 vcc, 0x100, v9
	s_cbranch_vccz .Lsig_d_got
	s_sleep 1
	v_cmp_gt_u32_e32 vcc, 0x20000, v10
	s_cbranch_vccnz .Lsig_d_spin
.Lsig_d_got:
	buffer_inv sc1
	s_waitcnt vmcnt(0)
.Lsig_d_skip:
	s_and_b64 vcc, exec, s[28:29]
	v_writelane_b32 v253, s43, 58
	v_writelane_b32 v252, s39, 30
	s_cbranch_vccnz .LBB0_420
	v_mov_b32_e32 v0, v190
	s_lshl_b32 s46, s96, 10
	v_add_u32_e32 v32, 0xffffff00, v0
	s_add_i32 s58, s46, -1
	v_ashrrev_i32_e32 v2, 4, v32
	v_lshlrev_b32_e32 v1, 2, v0
	v_add_u32_e32 v2, s58, v2
	s_movk_i32 s36, 0x510
	v_and_b32_e32 v1, 60, v1
	v_cmp_gt_i32_e32 vcc, s36, v0
	v_cmp_lt_i32_e64 s[36:37], -1, v2
	s_and_b64 s[38:39], vcc, s[36:37]
	v_mov_b32_e32 v4, 0
	v_lshlrev_b32_e32 v24, 2, v1
	v_mov_b32_e32 v8, 0
	v_mov_b32_e32 v9, 0
	v_mov_b32_e32 v10, 0
	v_mov_b32_e32 v11, 0
	s_and_saveexec_b64 s[36:37], s[38:39]
	s_cbranch_execz .LBB0_369
	v_lshlrev_b64 v[6:7], 10, v[2:3]
	v_readlane_b32 s38, v252, 27
	v_lshl_add_u64 v[6:7], s[54:55], 0, v[6:7]
	s_lshl_b32 s92, s38, 2
	v_lshl_add_u64 v[6:7], v[6:7], 0, s[92:93]
	v_mov_b32_e32 v25, v3
	v_lshl_add_u64 v[6:7], v[6:7], 0, v[24:25]
	global_load_dwordx4 v[8:11], v[6:7], off
	v_readlane_b32 s39, v252, 28
